# cost-weighted re-spacing of the PV-phase VALU (exp/cvt) around the 16 MFMAs, with transcendental and MFMA-operand wait states re-derived
# speedup vs baseline: 1.0010x; 1.0010x over previous
.LBB0_302:
	s_addk_i32 s7, 0x2400
	v_add3_u32 v0, v198, s7, v200
	s_add_i32 s15, s14, -2
	s_cmp_ge_u32 s15, s23
	v_cvt_pk_bf16_f32 v166, v246, v202
	v_cvt_pk_bf16_f32 v167, v203, v204
	v_cvt_pk_bf16_f32 v168, v205, v206
	v_cvt_pk_bf16_f32 v169, v207, v208
	s_nop 0
	s_waitcnt lgkmcnt(4)
	v_mfma_f32_32x32x16_bf16 v[18:33], v[238:241], v[166:169], v[18:33]
	ds_read_b128 v[238:241], v247 offset:57920
	v_exp_f32_e32 v209, v58
	v_exp_f32_e32 v210, v59
	s_nop 0
	v_cvt_pk_bf16_f32 v162, v209, v210
	s_waitcnt lgkmcnt(4)
	v_mfma_f32_32x32x16_bf16 v[2:17], v[242:245], v[166:169], v[2:17]
	ds_read_b128 v[242:245], v247 offset:53344
	v_cvt_pk_bf16_f32 v163, v211, v212
	v_cvt_pk_bf16_f32 v164, v213, v214
	v_cvt_pk_bf16_f32 v165, v215, v216
	v_exp_f32_e32 v217, v66
	v_exp_f32_e32 v218, v67
	v_exp_f32_e32 v219, v68
	s_waitcnt lgkmcnt(4)
	v_mfma_f32_32x32x16_bf16 v[18:33], v[226:229], v[162:165], v[18:33]
	ds_read_b128 v[226:229], v247 offset:57952
	v_exp_f32_e32 v220, v69
	v_exp_f32_e32 v221, v70
	v_exp_f32_e32 v222, v71
	v_exp_f32_e32 v223, v72
	s_waitcnt lgkmcnt(4)
	v_mfma_f32_32x32x16_bf16 v[2:17], v[230:233], v[162:165], v[2:17]
	ds_read_b128 v[230:233], v0 offset:53248
	v_exp_f32_e32 v224, v73
	v_cvt_pk_bf16_f32 v70, v217, v218
	v_cvt_pk_bf16_f32 v71, v219, v220
	v_cvt_pk_bf16_f32 v72, v221, v222
	v_cvt_pk_bf16_f32 v73, v223, v224
	v_exp_f32_e32 v74, v74
	s_waitcnt lgkmcnt(4)
	v_mfma_f32_32x32x16_bf16 v[18:33], v[234:237], v[70:73], v[18:33]
	ds_read_b128 v[234:237], v0 offset:57856
	v_exp_f32_e32 v75, v75
	v_exp_f32_e32 v76, v76
	v_exp_f32_e32 v77, v77
	v_exp_f32_e32 v78, v78
	s_waitcnt lgkmcnt(4)
	v_mfma_f32_32x32x16_bf16 v[2:17], v[238:241], v[70:73], v[2:17]
	ds_read_b128 v[238:241], v0 offset:53280
	v_exp_f32_e32 v79, v79
	v_exp_f32_e32 v80, v80
	v_exp_f32_e32 v81, v81
	v_cvt_pk_bf16_f32 v66, v74, v75
	v_cvt_pk_bf16_f32 v67, v76, v77
	v_cvt_pk_bf16_f32 v68, v78, v79
	v_cvt_pk_bf16_f32 v69, v80, v81
	s_nop 0
	s_waitcnt lgkmcnt(4)
	v_mfma_f32_32x32x16_bf16 v[18:33], v[242:245], v[66:69], v[18:33]
	ds_read_b128 v[242:245], v0 offset:57888
	v_exp_f32_e32 v82, v82
	v_exp_f32_e32 v83, v83
	v_exp_f32_e32 v84, v84
	s_waitcnt lgkmcnt(4)
	v_mfma_f32_32x32x16_bf16 v[2:17], v[226:229], v[66:69], v[2:17]
	ds_read_b128 v[226:229], v0 offset:53312
	v_exp_f32_e32 v85, v85
	v_exp_f32_e32 v86, v86
	v_exp_f32_e32 v87, v87
	v_exp_f32_e32 v88, v88
	v_exp_f32_e32 v89, v89
	v_cvt_pk_bf16_f32 v62, v82, v83
	v_cvt_pk_bf16_f32 v63, v84, v85
	v_cvt_pk_bf16_f32 v64, v86, v87
	v_cvt_pk_bf16_f32 v65, v88, v89
	s_nop 0
	s_waitcnt lgkmcnt(4)
	v_mfma_f32_32x32x16_bf16 v[18:33], v[230:233], v[62:65], v[18:33]
	ds_read_b128 v[230:233], v0 offset:57920
	v_exp_f32_e32 v90, v90
	v_exp_f32_e32 v91, v91
	s_waitcnt lgkmcnt(4)
	v_mfma_f32_32x32x16_bf16 v[2:17], v[234:237], v[62:65], v[2:17]
	ds_read_b128 v[234:237], v0 offset:53344
	v_exp_f32_e32 v92, v92
	v_exp_f32_e32 v93, v93
	v_exp_f32_e32 v94, v94
	v_exp_f32_e32 v95, v95
	v_exp_f32_e32 v96, v96
	v_exp_f32_e32 v97, v97
	v_cvt_pk_bf16_f32 v58, v90, v91
	v_cvt_pk_bf16_f32 v59, v92, v93
	v_cvt_pk_bf16_f32 v60, v94, v95
	v_cvt_pk_bf16_f32 v61, v96, v97
	s_nop 0
	s_waitcnt lgkmcnt(4)
	v_mfma_f32_32x32x16_bf16 v[18:33], v[238:241], v[58:61], v[18:33]
	ds_read_b128 v[238:241], v0 offset:57952
	s_waitcnt lgkmcnt(4)
	v_mfma_f32_32x32x16_bf16 v[2:17], v[242:245], v[58:61], v[2:17]
	v_exp_f32_e32 v98, v98
	v_exp_f32_e32 v99, v99
	v_exp_f32_e32 v100, v100
	v_exp_f32_e32 v101, v101
	v_exp_f32_e32 v102, v102
	v_exp_f32_e32 v103, v103
	v_exp_f32_e32 v104, v104
	v_exp_f32_e32 v105, v105
	v_cvt_pk_bf16_f32 v54, v98, v99
	v_cvt_pk_bf16_f32 v55, v100, v101
	v_cvt_pk_bf16_f32 v56, v102, v103
	v_cvt_pk_bf16_f32 v57, v104, v105
	s_nop 0
	s_waitcnt lgkmcnt(3)
	v_mfma_f32_32x32x16_bf16 v[18:33], v[226:229], v[54:57], v[18:33]
	s_waitcnt lgkmcnt(2)
	v_mfma_f32_32x32x16_bf16 v[2:17], v[230:233], v[54:57], v[2:17]
	v_exp_f32_e32 v106, v106
	v_exp_f32_e32 v107, v107
	v_exp_f32_e32 v108, v108
	v_exp_f32_e32 v109, v109
	v_exp_f32_e32 v110, v110
	v_exp_f32_e32 v111, v111
	v_exp_f32_e32 v112, v112
	v_exp_f32_e32 v113, v113
	v_cvt_pk_bf16_f32 v50, v106, v107
	v_cvt_pk_bf16_f32 v51, v108, v109
	v_cvt_pk_bf16_f32 v52, v110, v111
	v_cvt_pk_bf16_f32 v53, v112, v113
	s_nop 0
	s_waitcnt lgkmcnt(1)
	v_mfma_f32_32x32x16_bf16 v[18:33], v[234:237], v[50:53], v[18:33]
	s_waitcnt lgkmcnt(0)
	v_mfma_f32_32x32x16_bf16 v[2:17], v[238:241], v[50:53], v[2:17]
	s_branch .LBB0_299

.LBB0_350:
	s_add_i32 s13, s12, -2
	s_cmp_ge_u32 s13, s23
	v_exp_f32_e32 v166, v98
	v_exp_f32_e32 v167, v99
	v_exp_f32_e32 v168, v100
	v_exp_f32_e32 v169, v101
	v_exp_f32_e32 v170, v102
	v_exp_f32_e32 v171, v103
	v_exp_f32_e32 v172, v104
	v_exp_f32_e32 v173, v105
	v_cvt_pk_bf16_f32 v146, v166, v167
	v_cvt_pk_bf16_f32 v147, v168, v169
	v_cvt_pk_bf16_f32 v148, v170, v171
	v_cvt_pk_bf16_f32 v149, v172, v173
	s_nop 0
	s_waitcnt lgkmcnt(5)
	v_mfma_f32_32x32x16_bf16 v[18:33], v[206:209], v[146:149], v[18:33]
	ds_read_b128 v[206:209], v0 offset:36960
	s_waitcnt lgkmcnt(5)
	v_mfma_f32_32x32x16_bf16 v[2:17], v[210:213], v[146:149], v[2:17]
	ds_read_b128 v[210:213], v0 offset:41568
	v_exp_f32_e32 v106, v106
	v_exp_f32_e32 v107, v107
	v_exp_f32_e32 v108, v108
	v_exp_f32_e32 v109, v109
	v_exp_f32_e32 v110, v110
	v_exp_f32_e32 v111, v111
	v_exp_f32_e32 v112, v112
	v_exp_f32_e32 v113, v113
	v_cvt_pk_bf16_f32 v102, v106, v107
	v_cvt_pk_bf16_f32 v103, v108, v109
	v_cvt_pk_bf16_f32 v104, v110, v111
	v_cvt_pk_bf16_f32 v105, v112, v113
	s_nop 0
	s_waitcnt lgkmcnt(5)
	v_mfma_f32_32x32x16_bf16 v[18:33], v[222:225], v[102:105], v[18:33]
	ds_read_b128 v[222:225], v0 offset:46080
	s_waitcnt lgkmcnt(5)
	v_mfma_f32_32x32x16_bf16 v[2:17], v[226:229], v[102:105], v[2:17]
	ds_read_b128 v[226:229], v0 offset:50688
	v_exp_f32_e32 v174, v66
	v_exp_f32_e32 v175, v67
	v_exp_f32_e32 v176, v68
	v_exp_f32_e32 v177, v69
	v_exp_f32_e32 v178, v70
	v_exp_f32_e32 v179, v71
	v_exp_f32_e32 v191, v72
	v_exp_f32_e32 v192, v73
	v_cvt_pk_bf16_f32 v98, v174, v175
	v_cvt_pk_bf16_f32 v99, v176, v177
	v_cvt_pk_bf16_f32 v100, v178, v179
	v_cvt_pk_bf16_f32 v101, v191, v192
	s_nop 0
	s_waitcnt lgkmcnt(5)
	v_mfma_f32_32x32x16_bf16 v[18:33], v[230:233], v[98:101], v[18:33]
	ds_read_b128 v[230:233], v0 offset:46112
	s_waitcnt lgkmcnt(5)
	v_mfma_f32_32x32x16_bf16 v[2:17], v[234:237], v[98:101], v[2:17]
	ds_read_b128 v[234:237], v0 offset:50720
	v_exp_f32_e32 v74, v74
	v_exp_f32_e32 v75, v75
	v_exp_f32_e32 v76, v76
	v_exp_f32_e32 v77, v77
	v_exp_f32_e32 v78, v78
	v_exp_f32_e32 v79, v79
	v_exp_f32_e32 v80, v80
	v_exp_f32_e32 v81, v81
	v_cvt_pk_bf16_f32 v70, v74, v75
	v_cvt_pk_bf16_f32 v71, v76, v77
	v_cvt_pk_bf16_f32 v72, v78, v79
	v_cvt_pk_bf16_f32 v73, v80, v81
	s_nop 0
	s_waitcnt lgkmcnt(5)
	v_mfma_f32_32x32x16_bf16 v[18:33], v[206:209], v[70:73], v[18:33]
	ds_read_b128 v[206:209], v0 offset:46144
	s_waitcnt lgkmcnt(5)
	v_mfma_f32_32x32x16_bf16 v[2:17], v[210:213], v[70:73], v[2:17]
	ds_read_b128 v[210:213], v0 offset:50752
	v_exp_f32_e32 v193, v50
	v_exp_f32_e32 v194, v51
	v_exp_f32_e32 v195, v52
	v_cvt_pk_bf16_f32 v66, v193, v194
	v_cvt_pk_bf16_f32 v67, v195, v196
	v_cvt_pk_bf16_f32 v68, v197, v198
	v_cvt_pk_bf16_f32 v69, v199, v200
	s_nop 0
	s_waitcnt lgkmcnt(5)
	v_mfma_f32_32x32x16_bf16 v[18:33], v[222:225], v[66:69], v[18:33]
	ds_read_b128 v[222:225], v0 offset:46176
	s_waitcnt lgkmcnt(5)
	v_mfma_f32_32x32x16_bf16 v[2:17], v[226:229], v[66:69], v[2:17]
	ds_read_b128 v[226:229], v0 offset:50784
	v_exp_f32_e32 v201, v58
	v_exp_f32_e32 v202, v59
	v_exp_f32_e32 v203, v60
	v_exp_f32_e32 v62, v62
	v_exp_f32_e32 v63, v63
	v_exp_f32_e32 v64, v64
	v_exp_f32_e32 v65, v65
	v_cvt_pk_bf16_f32 v58, v201, v202
	v_cvt_pk_bf16_f32 v59, v203, v204
	v_cvt_pk_bf16_f32 v60, v62, v63
	v_cvt_pk_bf16_f32 v61, v64, v65
	s_nop 0
	s_waitcnt lgkmcnt(5)
	v_mfma_f32_32x32x16_bf16 v[18:33], v[230:233], v[58:61], v[18:33]
	s_waitcnt lgkmcnt(4)
	v_mfma_f32_32x32x16_bf16 v[2:17], v[234:237], v[58:61], v[2:17]
	v_exp_f32_e32 v82, v82
	v_exp_f32_e32 v83, v83
	v_exp_f32_e32 v84, v84
	v_exp_f32_e32 v85, v85
	v_exp_f32_e32 v86, v86
	v_exp_f32_e32 v87, v87
	v_exp_f32_e32 v88, v88
	v_exp_f32_e32 v89, v89
	v_cvt_pk_bf16_f32 v54, v82, v83
	v_cvt_pk_bf16_f32 v55, v84, v85
	v_cvt_pk_bf16_f32 v56, v86, v87
	v_cvt_pk_bf16_f32 v57, v88, v89
	s_nop 0
	s_waitcnt lgkmcnt(3)
	v_mfma_f32_32x32x16_bf16 v[18:33], v[206:209], v[54:57], v[18:33]
	s_waitcnt lgkmcnt(2)
	v_mfma_f32_32x32x16_bf16 v[2:17], v[210:213], v[54:57], v[2:17]
	v_exp_f32_e32 v90, v90
	v_exp_f32_e32 v91, v91
	v_exp_f32_e32 v92, v92
	v_exp_f32_e32 v93, v93
	v_exp_f32_e32 v94, v94
	v_exp_f32_e32 v95, v95
	v_exp_f32_e32 v96, v96
	v_exp_f32_e32 v97, v97
	v_cvt_pk_bf16_f32 v50, v90, v91
	v_cvt_pk_bf16_f32 v51, v92, v93
	v_cvt_pk_bf16_f32 v52, v94, v95
	v_cvt_pk_bf16_f32 v53, v96, v97
	s_nop 0
	s_waitcnt lgkmcnt(1)
	v_mfma_f32_32x32x16_bf16 v[18:33], v[222:225], v[50:53], v[18:33]
	s_waitcnt lgkmcnt(0)
	v_mfma_f32_32x32x16_bf16 v[2:17], v[226:229], v[50:53], v[2:17]
	s_branch .LBB0_347
